# strategy 7 instruction selection: w_in gate epilogue floor max(rint(255 sigmoid),1) folded into a clamp on the preceding fma (v_max deleted, results bit-identical); on top of k-inner Gray MFMA order
# speedup vs baseline: 1.0014x; 1.0005x over previous
.LBB0_291:
	s_andn2_b64 vcc, exec, s[36:37]
	s_cbranch_vccnz .LBB0_293
	s_sub_i32 s36, s29, 18
	v_lshl_or_b32 v202, s36, 8, v149
	v_lshl_add_u64 v[138:139], v[202:203], 2, s[4:5]
	global_load_dwordx4 v[158:161], v[138:139], off
	global_load_dwordx4 v[166:169], v[138:139], off offset:16
	global_load_dwordx4 v[170:173], v[138:139], off offset:512
	global_load_dwordx4 v[174:177], v[138:139], off offset:528
	s_lshr_b32 s35, s36, 3
	s_mulk_i32 s35, 0xc0
	s_add_i32 s34, s35, s34
	s_ashr_i32 s35, s34, 31
	s_lshl_b64 s[34:35], s[34:35], 19
	s_add_u32 s34, s38, s34
	s_addc_u32 s35, s39, s35
	s_lshl_b32 s36, s36, 16
	s_and_b32 s36, s36, 0x70000
	s_add_u32 s34, s34, s36
	s_addc_u32 s35, s35, 0
	s_add_u32 s34, s34, s26
	s_addc_u32 s35, s35, s27
	s_lshl_b32 s36, s60, 2
	s_add_i32 s36, s67, s36
	v_lshl_add_u32 v165, v146, 2, s36
	ds_read2_b32 v[178:179], v165 offset1:16
	v_mov_b32_e32 v135, v203
	v_lshl_add_u64 v[138:139], s[34:35], 0, v[134:135]
	s_waitcnt lgkmcnt(0)
	v_mul_f32_e32 v178, 0xbfb8aa3b, v178
	s_waitcnt vmcnt(0)
	v_mul_f32_e32 v141, 0xbfb8aa3b, v158
	v_mul_f32_e32 v140, 0xbfb8aa3b, v166
	v_mul_f32_e32 v137, 0xbfb8aa3b, v170
	v_mul_f32_e32 v135, 0xbfb8aa3b, v174
	v_mul_f32_e32 v156, 0xbfb8aa3b, v159
	v_mul_f32_e32 v155, 0xbfb8aa3b, v167
	v_mul_f32_e32 v154, 0xbfb8aa3b, v171
	v_mul_f32_e32 v153, 0xbfb8aa3b, v175
	v_mul_f32_e32 v159, 0xbfb8aa3b, v168
	v_mul_f32_e32 v163, 0xbfb8aa3b, v169
	v_fma_f32 v166, v126, v178, v141
	v_fma_f32 v167, v122, v178, v140
	v_fma_f32 v168, v118, v178, v137
	v_fma_f32 v169, v114, v178, v135
	v_mul_f32_e32 v160, 0xbfb8aa3b, v160
	v_mul_f32_e32 v158, 0xbfb8aa3b, v172
	v_mul_f32_e32 v157, 0xbfb8aa3b, v176
	v_mul_f32_e32 v162, 0xbfb8aa3b, v173
	v_fma_f32 v170, v127, v178, v156
	v_fma_f32 v171, v123, v178, v155
	v_fma_f32 v172, v119, v178, v154
	v_fma_f32 v173, v115, v178, v153
	v_exp_f32_e32 v166, v166
	v_exp_f32_e32 v167, v167
	v_exp_f32_e32 v168, v168
	v_exp_f32_e32 v169, v169
	v_mul_f32_e32 v164, 0xbfb8aa3b, v161
	v_mul_f32_e32 v161, 0xbfb8aa3b, v177
	v_fma_f32 v174, v128, v178, v160
	v_fma_f32 v175, v124, v178, v159
	v_fma_f32 v176, v120, v178, v158
	v_fma_f32 v177, v116, v178, v157
	v_exp_f32_e32 v170, v170
	v_exp_f32_e32 v171, v171
	v_exp_f32_e32 v172, v172
	v_exp_f32_e32 v173, v173
	v_fma_f32 v180, v129, v178, v164
	v_fma_f32 v181, v125, v178, v163
	v_fma_f32 v182, v121, v178, v162
	v_fma_f32 v178, v117, v178, v161
	v_exp_f32_e32 v174, v174
	v_exp_f32_e32 v175, v175
	v_exp_f32_e32 v176, v176
	v_exp_f32_e32 v177, v177
	v_exp_f32_e32 v180, v180
	v_exp_f32_e32 v181, v181
	v_exp_f32_e32 v182, v182
	v_exp_f32_e32 v178, v178
	v_fma_f32 v166, v166, v229, v229 clamp
	v_fma_f32 v167, v167, v229, v229 clamp
	v_fma_f32 v168, v168, v229, v229 clamp
	v_fma_f32 v169, v169, v229, v229 clamp
	v_fma_f32 v170, v170, v229, v229 clamp
	v_fma_f32 v171, v171, v229, v229 clamp
	v_fma_f32 v172, v172, v229, v229 clamp
	v_fma_f32 v173, v173, v229, v229 clamp
	v_rcp_f32_e32 v166, v166
	v_rcp_f32_e32 v167, v167
	v_rcp_f32_e32 v168, v168
	v_rcp_f32_e32 v169, v169
	v_fma_f32 v174, v174, v229, v229 clamp
	v_fma_f32 v175, v175, v229, v229 clamp
	v_fma_f32 v176, v176, v229, v229 clamp
	v_fma_f32 v177, v177, v229, v229 clamp
	v_rcp_f32_e32 v170, v170
	v_rcp_f32_e32 v171, v171
	v_rcp_f32_e32 v172, v172
	v_rcp_f32_e32 v173, v173
	v_fma_f32 v180, v180, v229, v229 clamp
	v_fma_f32 v181, v181, v229, v229 clamp
	v_fma_f32 v182, v182, v229, v229 clamp
	v_fma_f32 v178, v178, v229, v229 clamp
	v_rcp_f32_e32 v174, v174
	v_rcp_f32_e32 v175, v175
	v_rcp_f32_e32 v176, v176
	v_rcp_f32_e32 v177, v177
	v_rcp_f32_e32 v180, v180
	v_rcp_f32_e32 v181, v181
	v_rcp_f32_e32 v182, v182
	v_rcp_f32_e32 v178, v178
	v_rndne_f32_e32 v166, v166
	v_rndne_f32_e32 v167, v167
	v_rndne_f32_e32 v168, v168
	v_rndne_f32_e32 v169, v169
	v_rndne_f32_e32 v170, v170
	v_rndne_f32_e32 v171, v171
	v_rndne_f32_e32 v172, v172
	v_rndne_f32_e32 v173, v173
	v_rndne_f32_e32 v174, v174
	v_rndne_f32_e32 v175, v175
	v_rndne_f32_e32 v176, v176
	v_rndne_f32_e32 v177, v177
	v_cvt_pk_u8_f32 v166, v166, 0, 0
	v_cvt_pk_u8_f32 v167, v167, 0, 0
	v_cvt_pk_u8_f32 v168, v168, 0, 0
	v_cvt_pk_u8_f32 v169, v169, 0, 0
	v_rndne_f32_e32 v180, v180
	v_rndne_f32_e32 v181, v181
	v_rndne_f32_e32 v182, v182
	v_rndne_f32_e32 v178, v178
	v_cvt_pk_u8_f32 v166, v170, 1, v166
	v_cvt_pk_u8_f32 v167, v171, 1, v167
	v_cvt_pk_u8_f32 v168, v172, 1, v168
	v_cvt_pk_u8_f32 v169, v173, 1, v169
	v_cvt_pk_u8_f32 v166, v174, 2, v166
	v_cvt_pk_u8_f32 v167, v175, 2, v167
	v_cvt_pk_u8_f32 v168, v176, 2, v168
	v_cvt_pk_u8_f32 v169, v177, 2, v169
	v_cvt_pk_u8_f32 v166, v180, 3, v166
	v_cvt_pk_u8_f32 v167, v181, 3, v167
	v_cvt_pk_u8_f32 v168, v182, 3, v168
	v_cvt_pk_u8_f32 v169, v178, 3, v169
	global_store_dwordx4 v134, v[166:169], s[34:35]
	s_nop 1
	v_mul_f32_e32 v166, 0xbfb8aa3b, v179
	v_fma_f32 v167, v110, v166, v141
	v_fma_f32 v168, v106, v166, v140
	v_fma_f32 v169, v102, v166, v137
	v_fma_f32 v170, v98, v166, v135
	v_fma_f32 v171, v111, v166, v156
	v_fma_f32 v172, v107, v166, v155
	v_fma_f32 v173, v103, v166, v154
	v_fma_f32 v174, v99, v166, v153
	v_fma_f32 v175, v112, v166, v160
	v_fma_f32 v176, v108, v166, v159
	v_fma_f32 v177, v104, v166, v158
	v_fma_f32 v178, v100, v166, v157
	v_fma_f32 v179, v113, v166, v164
	v_fma_f32 v180, v109, v166, v163
	v_fma_f32 v181, v105, v166, v162
	v_fma_f32 v166, v101, v166, v161
	v_exp_f32_e32 v167, v167
	v_exp_f32_e32 v171, v171
	v_exp_f32_e32 v168, v168
	v_exp_f32_e32 v169, v169
	v_exp_f32_e32 v170, v170
	v_exp_f32_e32 v166, v166
	v_exp_f32_e32 v172, v172
	v_exp_f32_e32 v173, v173
	v_exp_f32_e32 v174, v174
	v_exp_f32_e32 v175, v175
	v_exp_f32_e32 v176, v176
	v_exp_f32_e32 v177, v177
	v_exp_f32_e32 v178, v178
	v_fma_f32 v167, v167, v229, v229 clamp
	v_exp_f32_e32 v179, v179
	v_exp_f32_e32 v180, v180
	v_exp_f32_e32 v181, v181
	v_fma_f32 v171, v171, v229, v229 clamp
	v_fma_f32 v168, v168, v229, v229 clamp
	v_fma_f32 v169, v169, v229, v229 clamp
	v_fma_f32 v170, v170, v229, v229 clamp
	v_fma_f32 v166, v166, v229, v229 clamp
	v_rcp_f32_e32 v167, v167
	v_rcp_f32_e32 v171, v171
	v_rcp_f32_e32 v168, v168
	v_rcp_f32_e32 v169, v169
	v_rcp_f32_e32 v170, v170
	v_rcp_f32_e32 v166, v166
	v_fma_f32 v172, v172, v229, v229 clamp
	v_fma_f32 v173, v173, v229, v229 clamp
	v_fma_f32 v174, v174, v229, v229 clamp
	v_fma_f32 v175, v175, v229, v229 clamp
	v_fma_f32 v176, v176, v229, v229 clamp
	v_fma_f32 v177, v177, v229, v229 clamp
	v_fma_f32 v178, v178, v229, v229 clamp
	v_rcp_f32_e32 v172, v172
	v_rcp_f32_e32 v173, v173
	v_rcp_f32_e32 v174, v174
	v_fma_f32 v179, v179, v229, v229 clamp
	v_fma_f32 v180, v180, v229, v229 clamp
	v_fma_f32 v181, v181, v229, v229 clamp
	v_rcp_f32_e32 v175, v175
	v_rcp_f32_e32 v176, v176
	v_rcp_f32_e32 v177, v177
	v_rcp_f32_e32 v178, v178
	v_rndne_f32_e32 v167, v167
	v_rcp_f32_e32 v179, v179
	v_rcp_f32_e32 v180, v180
	v_rcp_f32_e32 v181, v181
	v_rndne_f32_e32 v171, v171
	v_rndne_f32_e32 v168, v168
	v_rndne_f32_e32 v169, v169
	v_rndne_f32_e32 v170, v170
	v_rndne_f32_e32 v166, v166
	v_max_f32_e32 v182, 1.0, v166
	v_cvt_pk_u8_f32 v166, v167, 0, 0
	v_rndne_f32_e32 v172, v172
	v_rndne_f32_e32 v173, v173
	v_rndne_f32_e32 v174, v174
	v_cvt_pk_u8_f32 v166, v171, 1, v166
	v_cvt_pk_u8_f32 v167, v168, 0, 0
	v_cvt_pk_u8_f32 v168, v169, 0, 0
	v_cvt_pk_u8_f32 v169, v170, 0, 0
	ds_read2_b32 v[170:171], v165 offset0:32 offset1:48
	v_rndne_f32_e32 v175, v175
	v_rndne_f32_e32 v176, v176
	v_rndne_f32_e32 v177, v177
	v_rndne_f32_e32 v178, v178
	v_rndne_f32_e32 v179, v179
	v_rndne_f32_e32 v180, v180
	v_rndne_f32_e32 v181, v181
	v_cvt_pk_u8_f32 v167, v172, 1, v167
	v_cvt_pk_u8_f32 v168, v173, 1, v168
	v_cvt_pk_u8_f32 v169, v174, 1, v169
	v_cvt_pk_u8_f32 v166, v175, 2, v166
	v_cvt_pk_u8_f32 v167, v176, 2, v167
	v_cvt_pk_u8_f32 v168, v177, 2, v168
	v_cvt_pk_u8_f32 v169, v178, 2, v169
	v_cvt_pk_u8_f32 v166, v179, 3, v166
	v_cvt_pk_u8_f32 v167, v180, 3, v167
	v_cvt_pk_u8_f32 v168, v181, 3, v168
	v_cvt_pk_u8_f32 v169, v182, 3, v169
	global_store_dwordx4 v134, v[166:169], s[34:35] offset:1024
	s_waitcnt lgkmcnt(0)
	s_nop 0
	v_mul_f32_e32 v166, 0xbfb8aa3b, v170
	v_fma_f32 v167, v94, v166, v141
	v_fma_f32 v168, v90, v166, v140
	v_fma_f32 v169, v86, v166, v137
	v_fma_f32 v170, v82, v166, v135
	v_fma_f32 v172, v95, v166, v156
	v_fma_f32 v173, v91, v166, v155
	v_fma_f32 v174, v87, v166, v154
	v_fma_f32 v175, v83, v166, v153
	v_fma_f32 v176, v96, v166, v160
	v_fma_f32 v177, v92, v166, v159
	v_fma_f32 v178, v88, v166, v158
	v_fma_f32 v179, v84, v166, v157
	v_fma_f32 v180, v97, v166, v164
	v_fma_f32 v181, v93, v166, v163
	v_fma_f32 v182, v89, v166, v162
	v_fma_f32 v166, v85, v166, v161
	v_exp_f32_e32 v167, v167
	v_exp_f32_e32 v168, v168
	v_exp_f32_e32 v169, v169
	v_exp_f32_e32 v170, v170
	v_exp_f32_e32 v172, v172
	v_exp_f32_e32 v173, v173
	v_exp_f32_e32 v174, v174
	v_exp_f32_e32 v175, v175
	v_exp_f32_e32 v166, v166
	v_exp_f32_e32 v176, v176
	v_exp_f32_e32 v177, v177
	v_exp_f32_e32 v178, v178
	v_exp_f32_e32 v179, v179
	v_exp_f32_e32 v180, v180
	v_exp_f32_e32 v181, v181
	v_exp_f32_e32 v182, v182
	v_fma_f32 v167, v167, v229, v229 clamp
	v_fma_f32 v168, v168, v229, v229 clamp
	v_fma_f32 v169, v169, v229, v229 clamp
	v_fma_f32 v170, v170, v229, v229 clamp
	v_fma_f32 v172, v172, v229, v229 clamp
	v_fma_f32 v173, v173, v229, v229 clamp
	v_fma_f32 v174, v174, v229, v229 clamp
	v_fma_f32 v175, v175, v229, v229 clamp
	v_fma_f32 v166, v166, v229, v229 clamp
	v_rcp_f32_e32 v167, v167
	v_rcp_f32_e32 v168, v168
	v_rcp_f32_e32 v169, v169
	v_rcp_f32_e32 v170, v170
	v_fma_f32 v176, v176, v229, v229 clamp
	v_fma_f32 v177, v177, v229, v229 clamp
	v_fma_f32 v178, v178, v229, v229 clamp
	v_fma_f32 v179, v179, v229, v229 clamp
	v_rcp_f32_e32 v172, v172
	v_rcp_f32_e32 v173, v173
	v_rcp_f32_e32 v174, v174
	v_rcp_f32_e32 v175, v175
	v_rcp_f32_e32 v166, v166
	v_fma_f32 v180, v180, v229, v229 clamp
	v_fma_f32 v181, v181, v229, v229 clamp
	v_fma_f32 v182, v182, v229, v229 clamp
	v_rcp_f32_e32 v176, v176
	v_rcp_f32_e32 v177, v177
	v_rcp_f32_e32 v178, v178
	v_rcp_f32_e32 v179, v179
	v_rcp_f32_e32 v180, v180
	v_rcp_f32_e32 v181, v181
	v_rcp_f32_e32 v182, v182
	v_rndne_f32_e32 v167, v167
	v_rndne_f32_e32 v168, v168
	v_rndne_f32_e32 v169, v169
	v_rndne_f32_e32 v170, v170
	v_rndne_f32_e32 v172, v172
	v_rndne_f32_e32 v173, v173
	v_rndne_f32_e32 v174, v174
	v_rndne_f32_e32 v175, v175
	v_rndne_f32_e32 v166, v166
	v_rndne_f32_e32 v176, v176
	v_rndne_f32_e32 v177, v177
	v_rndne_f32_e32 v178, v178
	v_rndne_f32_e32 v179, v179
	v_max_f32_e32 v183, 1.0, v166
	v_cvt_pk_u8_f32 v166, v167, 0, 0
	v_cvt_pk_u8_f32 v167, v168, 0, 0
	v_cvt_pk_u8_f32 v168, v169, 0, 0
	v_cvt_pk_u8_f32 v169, v170, 0, 0
	v_rndne_f32_e32 v180, v180
	v_rndne_f32_e32 v181, v181
	v_rndne_f32_e32 v182, v182
	v_cvt_pk_u8_f32 v166, v172, 1, v166
	v_cvt_pk_u8_f32 v167, v173, 1, v167
	v_cvt_pk_u8_f32 v168, v174, 1, v168
	v_cvt_pk_u8_f32 v169, v175, 1, v169
	v_cvt_pk_u8_f32 v166, v176, 2, v166
	v_cvt_pk_u8_f32 v167, v177, 2, v167
	v_cvt_pk_u8_f32 v168, v178, 2, v168
	v_cvt_pk_u8_f32 v169, v179, 2, v169
	v_cvt_pk_u8_f32 v166, v180, 3, v166
	v_cvt_pk_u8_f32 v167, v181, 3, v167
	v_cvt_pk_u8_f32 v168, v182, 3, v168
	v_cvt_pk_u8_f32 v169, v183, 3, v169
	global_store_dwordx4 v134, v[166:169], s[34:35] offset:2048
	s_nop 1
	v_mul_f32_e32 v166, 0xbfb8aa3b, v171
	v_fma_f32 v167, v78, v166, v141
	v_fma_f32 v168, v74, v166, v140
	v_fma_f32 v169, v70, v166, v137
	v_fma_f32 v170, v66, v166, v135
	v_fma_f32 v171, v79, v166, v156
	v_fma_f32 v172, v75, v166, v155
	v_fma_f32 v173, v71, v166, v154
	v_fma_f32 v174, v67, v166, v153
	v_fma_f32 v175, v80, v166, v160
	v_fma_f32 v176, v76, v166, v159
	v_fma_f32 v177, v72, v166, v158
	v_fma_f32 v178, v68, v166, v157
	v_fma_f32 v179, v81, v166, v164
	v_fma_f32 v180, v77, v166, v163
	v_fma_f32 v181, v73, v166, v162
	v_fma_f32 v166, v69, v166, v161
	v_exp_f32_e32 v167, v167
	v_exp_f32_e32 v171, v171
	v_exp_f32_e32 v168, v168
	v_exp_f32_e32 v169, v169
	v_exp_f32_e32 v170, v170
	v_exp_f32_e32 v166, v166
	v_exp_f32_e32 v172, v172
	v_exp_f32_e32 v173, v173
	v_exp_f32_e32 v174, v174
	v_exp_f32_e32 v175, v175
	v_exp_f32_e32 v176, v176
	v_exp_f32_e32 v177, v177
	v_exp_f32_e32 v178, v178
	v_fma_f32 v167, v167, v229, v229 clamp
	v_exp_f32_e32 v179, v179
	v_exp_f32_e32 v180, v180
	v_exp_f32_e32 v181, v181
	v_fma_f32 v171, v171, v229, v229 clamp
	v_fma_f32 v168, v168, v229, v229 clamp
	v_fma_f32 v169, v169, v229, v229 clamp
	v_fma_f32 v170, v170, v229, v229 clamp
	v_fma_f32 v166, v166, v229, v229 clamp
	v_rcp_f32_e32 v167, v167
	v_rcp_f32_e32 v171, v171
	v_rcp_f32_e32 v168, v168
	v_rcp_f32_e32 v169, v169
	v_rcp_f32_e32 v170, v170
	v_rcp_f32_e32 v166, v166
	v_fma_f32 v172, v172, v229, v229 clamp
	v_fma_f32 v173, v173, v229, v229 clamp
	v_fma_f32 v174, v174, v229, v229 clamp
	v_fma_f32 v175, v175, v229, v229 clamp
	v_fma_f32 v176, v176, v229, v229 clamp
	v_fma_f32 v177, v177, v229, v229 clamp
	v_fma_f32 v178, v178, v229, v229 clamp
	v_rcp_f32_e32 v172, v172
	v_rcp_f32_e32 v173, v173
	v_rcp_f32_e32 v174, v174
	v_fma_f32 v179, v179, v229, v229 clamp
	v_fma_f32 v180, v180, v229, v229 clamp
	v_fma_f32 v181, v181, v229, v229 clamp
	v_rcp_f32_e32 v175, v175
	v_rcp_f32_e32 v176, v176
	v_rcp_f32_e32 v177, v177
	v_rcp_f32_e32 v178, v178
	v_rndne_f32_e32 v167, v167
	v_rcp_f32_e32 v179, v179
	v_rcp_f32_e32 v180, v180
	v_rcp_f32_e32 v181, v181
	v_rndne_f32_e32 v171, v171
	v_rndne_f32_e32 v168, v168
	v_rndne_f32_e32 v169, v169
	v_rndne_f32_e32 v170, v170
	v_rndne_f32_e32 v166, v166
	v_max_f32_e32 v182, 1.0, v166
	v_cvt_pk_u8_f32 v166, v167, 0, 0
	v_rndne_f32_e32 v172, v172
	v_rndne_f32_e32 v173, v173
	v_rndne_f32_e32 v174, v174
	v_cvt_pk_u8_f32 v166, v171, 1, v166
	v_cvt_pk_u8_f32 v167, v168, 0, 0
	v_cvt_pk_u8_f32 v168, v169, 0, 0
	v_cvt_pk_u8_f32 v169, v170, 0, 0
	ds_read2_b32 v[170:171], v165 offset0:128 offset1:144
	v_rndne_f32_e32 v175, v175
	v_rndne_f32_e32 v176, v176
	v_rndne_f32_e32 v177, v177
	v_rndne_f32_e32 v178, v178
	v_rndne_f32_e32 v179, v179
	v_rndne_f32_e32 v180, v180
	v_rndne_f32_e32 v181, v181
	v_cvt_pk_u8_f32 v167, v172, 1, v167
	v_cvt_pk_u8_f32 v168, v173, 1, v168
	v_cvt_pk_u8_f32 v169, v174, 1, v169
	v_cvt_pk_u8_f32 v166, v175, 2, v166
	v_cvt_pk_u8_f32 v167, v176, 2, v167
	v_cvt_pk_u8_f32 v168, v177, 2, v168
	v_cvt_pk_u8_f32 v169, v178, 2, v169
	v_cvt_pk_u8_f32 v166, v179, 3, v166
	v_cvt_pk_u8_f32 v167, v180, 3, v167
	v_cvt_pk_u8_f32 v168, v181, 3, v168
	v_cvt_pk_u8_f32 v169, v182, 3, v169
	global_store_dwordx4 v134, v[166:169], s[34:35] offset:3072
	s_movk_i32 s34, 0x1000
	v_add_co_u32_e32 v138, vcc, s34, v138
	s_waitcnt lgkmcnt(0)
	v_mul_f32_e32 v166, 0xbfb8aa3b, v170
	v_fma_f32 v167, v62, v166, v141
	v_fma_f32 v168, v58, v166, v140
	v_fma_f32 v169, v54, v166, v137
	v_fma_f32 v170, v50, v166, v135
	v_fma_f32 v172, v63, v166, v156
	v_fma_f32 v173, v59, v166, v155
	v_fma_f32 v174, v55, v166, v154
	v_fma_f32 v175, v51, v166, v153
	v_fma_f32 v176, v64, v166, v160
	v_fma_f32 v177, v60, v166, v159
	v_fma_f32 v178, v56, v166, v158
	v_fma_f32 v179, v52, v166, v157
	v_fma_f32 v180, v65, v166, v164
	v_fma_f32 v181, v61, v166, v163
	v_fma_f32 v182, v57, v166, v162
	v_fma_f32 v166, v53, v166, v161
	v_exp_f32_e32 v167, v167
	v_exp_f32_e32 v168, v168
	v_exp_f32_e32 v169, v169
	v_exp_f32_e32 v170, v170
	v_exp_f32_e32 v172, v172
	v_exp_f32_e32 v173, v173
	v_exp_f32_e32 v174, v174
	v_exp_f32_e32 v175, v175
	v_exp_f32_e32 v166, v166
	v_exp_f32_e32 v176, v176
	v_exp_f32_e32 v177, v177
	v_exp_f32_e32 v178, v178
	v_exp_f32_e32 v179, v179
	v_exp_f32_e32 v180, v180
	v_exp_f32_e32 v181, v181
	v_exp_f32_e32 v182, v182
	v_fma_f32 v167, v167, v229, v229 clamp
	v_fma_f32 v168, v168, v229, v229 clamp
	v_fma_f32 v169, v169, v229, v229 clamp
	v_fma_f32 v170, v170, v229, v229 clamp
	v_fma_f32 v172, v172, v229, v229 clamp
	v_fma_f32 v173, v173, v229, v229 clamp
	v_fma_f32 v174, v174, v229, v229 clamp
	v_fma_f32 v175, v175, v229, v229 clamp
	v_fma_f32 v166, v166, v229, v229 clamp
	v_rcp_f32_e32 v167, v167
	v_rcp_f32_e32 v168, v168
	v_rcp_f32_e32 v169, v169
	v_rcp_f32_e32 v170, v170
	v_fma_f32 v176, v176, v229, v229 clamp
	v_fma_f32 v177, v177, v229, v229 clamp
	v_fma_f32 v178, v178, v229, v229 clamp
	v_fma_f32 v179, v179, v229, v229 clamp
	v_rcp_f32_e32 v172, v172
	v_rcp_f32_e32 v173, v173
	v_rcp_f32_e32 v174, v174
	v_rcp_f32_e32 v175, v175
	v_rcp_f32_e32 v166, v166
	v_fma_f32 v180, v180, v229, v229 clamp
	v_fma_f32 v181, v181, v229, v229 clamp
	v_fma_f32 v182, v182, v229, v229 clamp
	v_rcp_f32_e32 v176, v176
	v_rcp_f32_e32 v177, v177
	v_rcp_f32_e32 v178, v178
	v_rcp_f32_e32 v179, v179
	v_rcp_f32_e32 v180, v180
	v_rcp_f32_e32 v181, v181
	v_rcp_f32_e32 v182, v182
	v_rndne_f32_e32 v167, v167
	v_rndne_f32_e32 v168, v168
	v_rndne_f32_e32 v169, v169
	v_rndne_f32_e32 v170, v170
	v_rndne_f32_e32 v172, v172
	v_rndne_f32_e32 v173, v173
	v_rndne_f32_e32 v174, v174
	v_rndne_f32_e32 v175, v175
	v_rndne_f32_e32 v166, v166
	v_rndne_f32_e32 v176, v176
	v_rndne_f32_e32 v177, v177
	v_rndne_f32_e32 v178, v178
	v_rndne_f32_e32 v179, v179
	v_max_f32_e32 v183, 1.0, v166
	v_cvt_pk_u8_f32 v166, v167, 0, 0
	v_cvt_pk_u8_f32 v167, v168, 0, 0
	v_cvt_pk_u8_f32 v168, v169, 0, 0
	v_cvt_pk_u8_f32 v169, v170, 0, 0
	v_rndne_f32_e32 v180, v180
	v_rndne_f32_e32 v181, v181
	v_rndne_f32_e32 v182, v182
	v_cvt_pk_u8_f32 v166, v172, 1, v166
	v_cvt_pk_u8_f32 v167, v173, 1, v167
	v_cvt_pk_u8_f32 v168, v174, 1, v168
	v_cvt_pk_u8_f32 v169, v175, 1, v169
	v_cvt_pk_u8_f32 v166, v176, 2, v166
	v_cvt_pk_u8_f32 v167, v177, 2, v167
	v_cvt_pk_u8_f32 v168, v178, 2, v168
	v_cvt_pk_u8_f32 v169, v179, 2, v169
	v_cvt_pk_u8_f32 v166, v180, 3, v166
	v_cvt_pk_u8_f32 v167, v181, 3, v167
	v_cvt_pk_u8_f32 v168, v182, 3, v168
	v_cvt_pk_u8_f32 v169, v183, 3, v169
	v_addc_co_u32_e32 v139, vcc, 0, v139, vcc
	global_store_dwordx4 v[138:139], v[166:169], off
	s_nop 1
	v_mul_f32_e32 v166, 0xbfb8aa3b, v171
	v_fma_f32 v167, v46, v166, v141
	v_fma_f32 v168, v42, v166, v140
	v_fma_f32 v169, v38, v166, v137
	v_fma_f32 v170, v34, v166, v135
	v_fma_f32 v171, v47, v166, v156
	v_fma_f32 v172, v43, v166, v155
	v_fma_f32 v173, v39, v166, v154
	v_fma_f32 v174, v35, v166, v153
	v_fma_f32 v175, v48, v166, v160
	v_fma_f32 v176, v44, v166, v159
	v_fma_f32 v177, v40, v166, v158
	v_fma_f32 v178, v36, v166, v157
	v_fma_f32 v179, v49, v166, v164
	v_fma_f32 v180, v45, v166, v163
	v_fma_f32 v181, v41, v166, v162
	v_fma_f32 v166, v37, v166, v161
	v_exp_f32_e32 v167, v167
	v_exp_f32_e32 v171, v171
	v_exp_f32_e32 v168, v168
	v_exp_f32_e32 v169, v169
	v_exp_f32_e32 v170, v170
	v_exp_f32_e32 v166, v166
	v_exp_f32_e32 v172, v172
	v_exp_f32_e32 v173, v173
	v_exp_f32_e32 v174, v174
	v_fma_f32 v167, v167, v229, v229 clamp
	v_exp_f32_e32 v175, v175
	v_exp_f32_e32 v176, v176
	v_exp_f32_e32 v177, v177
	v_exp_f32_e32 v178, v178
	v_fma_f32 v171, v171, v229, v229 clamp
	v_fma_f32 v168, v168, v229, v229 clamp
	v_fma_f32 v169, v169, v229, v229 clamp
	v_fma_f32 v170, v170, v229, v229 clamp
	v_fma_f32 v166, v166, v229, v229 clamp
	v_rcp_f32_e32 v167, v167
	v_exp_f32_e32 v179, v179
	v_exp_f32_e32 v180, v180
	v_exp_f32_e32 v181, v181
	v_rcp_f32_e32 v171, v171
	v_rcp_f32_e32 v168, v168
	v_rcp_f32_e32 v169, v169
	v_rcp_f32_e32 v170, v170
	v_rcp_f32_e32 v166, v166
	v_fma_f32 v172, v172, v229, v229 clamp
	v_fma_f32 v173, v173, v229, v229 clamp
	v_fma_f32 v174, v174, v229, v229 clamp
	v_fma_f32 v175, v175, v229, v229 clamp
	v_fma_f32 v176, v176, v229, v229 clamp
	v_fma_f32 v177, v177, v229, v229 clamp
	v_fma_f32 v178, v178, v229, v229 clamp
	v_rcp_f32_e32 v172, v172
	v_rcp_f32_e32 v173, v173
	v_rcp_f32_e32 v174, v174
	v_rndne_f32_e32 v167, v167
	v_fma_f32 v179, v179, v229, v229 clamp
	v_fma_f32 v180, v180, v229, v229 clamp
	v_fma_f32 v181, v181, v229, v229 clamp
	v_rcp_f32_e32 v175, v175
	v_rcp_f32_e32 v176, v176
	v_rcp_f32_e32 v177, v177
	v_rcp_f32_e32 v178, v178
	v_rndne_f32_e32 v171, v171
	v_rndne_f32_e32 v168, v168
	v_rndne_f32_e32 v169, v169
	v_rndne_f32_e32 v170, v170
	v_rndne_f32_e32 v166, v166
	v_rcp_f32_e32 v179, v179
	v_rcp_f32_e32 v180, v180
	v_rcp_f32_e32 v181, v181
	v_max_f32_e32 v182, 1.0, v166
	v_cvt_pk_u8_f32 v166, v167, 0, 0
	v_cvt_pk_u8_f32 v166, v171, 1, v166
	v_cvt_pk_u8_f32 v167, v168, 0, 0
	v_cvt_pk_u8_f32 v168, v169, 0, 0
	v_cvt_pk_u8_f32 v169, v170, 0, 0
	ds_read2_b32 v[170:171], v165 offset0:160 offset1:176
	v_rndne_f32_e32 v172, v172
	v_rndne_f32_e32 v173, v173
	v_rndne_f32_e32 v174, v174
	v_rndne_f32_e32 v175, v175
	v_rndne_f32_e32 v176, v176
	v_rndne_f32_e32 v177, v177
	v_rndne_f32_e32 v178, v178
	v_rndne_f32_e32 v179, v179
	v_rndne_f32_e32 v180, v180
	v_rndne_f32_e32 v181, v181
	v_cvt_pk_u8_f32 v167, v172, 1, v167
	v_cvt_pk_u8_f32 v168, v173, 1, v168
	v_cvt_pk_u8_f32 v165, v174, 1, v169
	v_cvt_pk_u8_f32 v166, v175, 2, v166
	v_cvt_pk_u8_f32 v167, v176, 2, v167
	v_cvt_pk_u8_f32 v168, v177, 2, v168
	v_cvt_pk_u8_f32 v165, v178, 2, v165
	v_cvt_pk_u8_f32 v166, v179, 3, v166
	v_cvt_pk_u8_f32 v167, v180, 3, v167
	v_cvt_pk_u8_f32 v168, v181, 3, v168
	v_cvt_pk_u8_f32 v169, v182, 3, v165
	s_waitcnt lgkmcnt(0)
	v_mul_f32_e32 v165, 0xbfb8aa3b, v170
	global_store_dwordx4 v[138:139], v[166:169], off offset:1024
	v_fma_f32 v174, v19, v165, v153
	v_fma_f32 v178, v20, v165, v157
	v_fma_f32 v169, v18, v165, v135
	v_exp_f32_e32 v169, v169
	v_exp_f32_e32 v174, v174
	v_fma_f32 v166, v30, v165, v141
	v_fma_f32 v167, v26, v165, v140
	v_fma_f32 v168, v22, v165, v137
	v_fma_f32 v170, v31, v165, v156
	v_fma_f32 v172, v27, v165, v155
	v_fma_f32 v173, v23, v165, v154
	v_fma_f32 v175, v32, v165, v160
	v_fma_f32 v176, v28, v165, v159
	v_fma_f32 v177, v24, v165, v158
	v_fma_f32 v179, v33, v165, v164
	v_fma_f32 v180, v29, v165, v163
	v_fma_f32 v181, v25, v165, v162
	v_fma_f32 v165, v21, v165, v161
	v_exp_f32_e32 v178, v178
	v_exp_f32_e32 v165, v165
	v_fma_f32 v169, v169, v229, v229 clamp
	v_fma_f32 v174, v174, v229, v229 clamp
	v_rcp_f32_e32 v169, v169
	v_fma_f32 v178, v178, v229, v229 clamp
	v_rcp_f32_e32 v174, v174
	v_fma_f32 v165, v165, v229, v229 clamp
	v_rcp_f32_e32 v178, v178
	v_rcp_f32_e32 v165, v165
	v_rndne_f32_e32 v169, v169
	v_rndne_f32_e32 v174, v174
	v_rndne_f32_e32 v178, v178
	v_cvt_pk_u8_f32 v169, v169, 0, 0
	v_rndne_f32_e32 v165, v165
	v_cvt_pk_u8_f32 v169, v174, 1, v169
	v_cvt_pk_u8_f32 v169, v178, 2, v169
	v_cvt_pk_u8_f32 v169, v165, 3, v169
	v_mul_f32_e32 v165, 0xbfb8aa3b, v171
	v_fmac_f32_e32 v154, v7, v165
	v_fmac_f32_e32 v141, v14, v165
	v_fmac_f32_e32 v140, v10, v165
	v_fmac_f32_e32 v137, v6, v165
	v_fmac_f32_e32 v135, v2, v165
	v_fmac_f32_e32 v158, v8, v165
	v_exp_f32_e32 v154, v154
	v_exp_f32_e32 v166, v166
	v_exp_f32_e32 v167, v167
	v_exp_f32_e32 v168, v168
	v_fmac_f32_e32 v156, v15, v165
	v_fmac_f32_e32 v155, v11, v165
	v_fmac_f32_e32 v153, v3, v165
	v_fmac_f32_e32 v162, v9, v165
	v_exp_f32_e32 v141, v141
	v_exp_f32_e32 v140, v140
	v_exp_f32_e32 v137, v137
	v_exp_f32_e32 v158, v158
	v_exp_f32_e32 v135, v135
	v_exp_f32_e32 v170, v170
	v_exp_f32_e32 v172, v172
	v_exp_f32_e32 v173, v173
	v_fmac_f32_e32 v160, v16, v165
	v_fmac_f32_e32 v159, v12, v165
	v_fmac_f32_e32 v157, v4, v165
	v_exp_f32_e32 v156, v156
	v_exp_f32_e32 v155, v155
	v_exp_f32_e32 v162, v162
	v_exp_f32_e32 v153, v153
	v_exp_f32_e32 v175, v175
	v_exp_f32_e32 v176, v176
	v_exp_f32_e32 v177, v177
	v_fmac_f32_e32 v164, v17, v165
	v_fmac_f32_e32 v163, v13, v165
	v_fmac_f32_e32 v161, v5, v165
	v_exp_f32_e32 v160, v160
	v_exp_f32_e32 v159, v159
	v_exp_f32_e32 v157, v157
	v_exp_f32_e32 v179, v179
	v_exp_f32_e32 v180, v180
	v_exp_f32_e32 v181, v181
	v_exp_f32_e32 v164, v164
	v_exp_f32_e32 v163, v163
	v_exp_f32_e32 v161, v161
	v_fma_f32 v154, v154, v229, v229 clamp
	v_fma_f32 v166, v166, v229, v229 clamp
	v_fma_f32 v167, v167, v229, v229 clamp
	v_fma_f32 v168, v168, v229, v229 clamp
	v_fma_f32 v141, v141, v229, v229 clamp
	v_fma_f32 v140, v140, v229, v229 clamp
	v_fma_f32 v137, v137, v229, v229 clamp
	v_fma_f32 v158, v158, v229, v229 clamp
	v_fma_f32 v135, v135, v229, v229 clamp
	v_rcp_f32_e32 v154, v154
	v_fma_f32 v170, v170, v229, v229 clamp
	v_fma_f32 v172, v172, v229, v229 clamp
	v_fma_f32 v173, v173, v229, v229 clamp
	v_rcp_f32_e32 v166, v166
	v_rcp_f32_e32 v167, v167
	v_rcp_f32_e32 v168, v168
	v_fma_f32 v156, v156, v229, v229 clamp
	v_fma_f32 v155, v155, v229, v229 clamp
	v_fma_f32 v162, v162, v229, v229 clamp
	v_fma_f32 v153, v153, v229, v229 clamp
	v_rcp_f32_e32 v141, v141
	v_rcp_f32_e32 v140, v140
	v_rcp_f32_e32 v137, v137
	v_rcp_f32_e32 v158, v158
	v_rcp_f32_e32 v135, v135
	v_fma_f32 v175, v175, v229, v229 clamp
	v_fma_f32 v176, v176, v229, v229 clamp
	v_fma_f32 v177, v177, v229, v229 clamp
	v_rcp_f32_e32 v170, v170
	v_rcp_f32_e32 v172, v172
	v_rcp_f32_e32 v173, v173
	v_fma_f32 v160, v160, v229, v229 clamp
	v_fma_f32 v159, v159, v229, v229 clamp
	v_fma_f32 v157, v157, v229, v229 clamp
	v_rcp_f32_e32 v156, v156
	v_rcp_f32_e32 v155, v155
	v_rcp_f32_e32 v162, v162
	v_rcp_f32_e32 v153, v153
	v_fma_f32 v179, v179, v229, v229 clamp
	v_fma_f32 v180, v180, v229, v229 clamp
	v_fma_f32 v181, v181, v229, v229 clamp
	v_rcp_f32_e32 v175, v175
	v_rcp_f32_e32 v176, v176
	v_rcp_f32_e32 v177, v177
	v_fma_f32 v164, v164, v229, v229 clamp
	v_fma_f32 v163, v163, v229, v229 clamp
	v_fma_f32 v161, v161, v229, v229 clamp
	v_rcp_f32_e32 v160, v160
	v_rcp_f32_e32 v159, v159
	v_rcp_f32_e32 v157, v157
	v_rcp_f32_e32 v179, v179
	v_rcp_f32_e32 v180, v180
	v_rcp_f32_e32 v181, v181
	v_rcp_f32_e32 v164, v164
	v_rcp_f32_e32 v163, v163
	v_rcp_f32_e32 v161, v161
	v_rndne_f32_e32 v154, v154
	v_rndne_f32_e32 v166, v166
	v_rndne_f32_e32 v167, v167
	v_rndne_f32_e32 v168, v168
	v_rndne_f32_e32 v141, v141
	v_rndne_f32_e32 v140, v140
	v_rndne_f32_e32 v137, v137
	v_max_f32_e32 v165, 1.0, v154
	v_rndne_f32_e32 v154, v158
	v_rndne_f32_e32 v135, v135
	v_rndne_f32_e32 v170, v170
	v_rndne_f32_e32 v172, v172
	v_rndne_f32_e32 v173, v173
	v_rndne_f32_e32 v156, v156
	v_rndne_f32_e32 v155, v155
	v_max_f32_e32 v158, 1.0, v154
	v_rndne_f32_e32 v154, v162
	v_rndne_f32_e32 v153, v153
	v_rndne_f32_e32 v175, v175
	v_rndne_f32_e32 v176, v176
	v_rndne_f32_e32 v177, v177
	v_cvt_pk_u8_f32 v166, v166, 0, 0
	v_cvt_pk_u8_f32 v167, v167, 0, 0
	v_cvt_pk_u8_f32 v168, v168, 0, 0
	v_rndne_f32_e32 v160, v160
	v_rndne_f32_e32 v159, v159
	v_max_f32_e32 v162, 1.0, v154
	v_rndne_f32_e32 v154, v157
	v_cvt_pk_u8_f32 v141, v141, 0, 0
	v_cvt_pk_u8_f32 v140, v140, 0, 0
	v_cvt_pk_u8_f32 v137, v137, 0, 0
	v_cvt_pk_u8_f32 v135, v135, 0, 0
	v_rndne_f32_e32 v179, v179
	v_rndne_f32_e32 v180, v180
	v_rndne_f32_e32 v181, v181
	v_cvt_pk_u8_f32 v166, v170, 1, v166
	v_cvt_pk_u8_f32 v167, v172, 1, v167
	v_cvt_pk_u8_f32 v168, v173, 1, v168
	v_rndne_f32_e32 v164, v164
	v_rndne_f32_e32 v163, v163
	v_max_f32_e32 v157, 1.0, v154
	v_rndne_f32_e32 v154, v161
	v_cvt_pk_u8_f32 v141, v156, 1, v141
	v_cvt_pk_u8_f32 v140, v155, 1, v140
	v_cvt_pk_u8_f32 v137, v165, 1, v137
	v_cvt_pk_u8_f32 v135, v153, 1, v135
	v_cvt_pk_u8_f32 v166, v175, 2, v166
	v_cvt_pk_u8_f32 v167, v176, 2, v167
	v_cvt_pk_u8_f32 v168, v177, 2, v168
	v_max_f32_e32 v161, 1.0, v154
	v_cvt_pk_u8_f32 v141, v160, 2, v141
	v_cvt_pk_u8_f32 v140, v159, 2, v140
	v_cvt_pk_u8_f32 v137, v158, 2, v137
	v_cvt_pk_u8_f32 v135, v157, 2, v135
	v_cvt_pk_u8_f32 v166, v179, 3, v166
	v_cvt_pk_u8_f32 v167, v180, 3, v167
	v_cvt_pk_u8_f32 v168, v181, 3, v168
	v_cvt_pk_u8_f32 v154, v164, 3, v141
	v_cvt_pk_u8_f32 v155, v163, 3, v140
	v_cvt_pk_u8_f32 v156, v162, 3, v137
	v_cvt_pk_u8_f32 v157, v161, 3, v135
	global_store_dwordx4 v[138:139], v[166:169], off offset:2048
	global_store_dwordx4 v[138:139], v[154:157], off offset:3072

.LBB0_322:
	s_andn2_b64 vcc, exec, s[2:3]
	s_cbranch_vccnz .LBB0_324
	v_readlane_b32 s2, v253, 29
	s_sub_i32 s6, s2, 18
	v_lshl_or_b32 v131, s6, 8, v135
	v_or_b32_e32 v202, s9, v131
	v_lshl_add_u64 v[136:137], v[202:203], 2, s[4:5]
	global_load_dwordx4 v[144:147], v[136:137], off
	global_load_dwordx4 v[152:155], v[136:137], off offset:16
	global_load_dwordx4 v[156:159], v[136:137], off offset:512
	global_load_dwordx4 v[160:163], v[136:137], off offset:528
	s_lshr_b32 s4, s6, 3
	v_readlane_b32 s10, v253, 17
	s_mulk_i32 s4, 0xc0
	v_readlane_b32 s11, v253, 18
	s_lshl_b32 s2, s13, 11
	s_lshl_b32 s3, s14, 9
	s_add_i32 s4, s4, s11
	s_or_b32 s2, s3, s2
	s_ashr_i32 s5, s4, 31
	s_ashr_i32 s3, s2, 31
	s_lshl_b64 s[4:5], s[4:5], 19
	s_add_u32 s4, s38, s4
	s_addc_u32 s5, s39, s5
	s_lshl_b32 s6, s6, 16
	s_and_b32 s6, s6, 0x70000
	s_add_u32 s4, s4, s6
	s_addc_u32 s5, s5, 0
	s_lshl_b64 s[2:3], s[2:3], 4
	s_add_u32 s2, s4, s2
	s_addc_u32 s3, s5, s3
	s_lshl_b32 s4, s12, 2
	s_add_i32 s4, s8, s4
	v_lshl_add_u32 v151, v134, 2, s4
	ds_read2_b32 v[164:165], v151 offset1:16
	v_lshlrev_b32_e32 v202, 4, v132
	v_lshl_add_u64 v[132:133], s[2:3], 0, v[202:203]
	s_waitcnt lgkmcnt(0)
	v_mul_f32_e32 v164, 0xbfb8aa3b, v164
	s_waitcnt vmcnt(0)
	v_mul_f32_e32 v138, 0xbfb8aa3b, v144
	v_mul_f32_e32 v137, 0xbfb8aa3b, v152
	v_mul_f32_e32 v136, 0xbfb8aa3b, v156
	v_mul_f32_e32 v131, 0xbfb8aa3b, v160
	v_mul_f32_e32 v142, 0xbfb8aa3b, v145
	v_mul_f32_e32 v141, 0xbfb8aa3b, v153
	v_mul_f32_e32 v140, 0xbfb8aa3b, v157
	v_mul_f32_e32 v139, 0xbfb8aa3b, v161
	v_mul_f32_e32 v145, 0xbfb8aa3b, v154
	v_mul_f32_e32 v149, 0xbfb8aa3b, v155
	v_fma_f32 v152, v126, v164, v138
	v_fma_f32 v153, v122, v164, v137
	v_fma_f32 v154, v118, v164, v136
	v_fma_f32 v155, v114, v164, v131
	v_mul_f32_e32 v146, 0xbfb8aa3b, v146
	v_mul_f32_e32 v144, 0xbfb8aa3b, v158
	v_mul_f32_e32 v143, 0xbfb8aa3b, v162
	v_mul_f32_e32 v148, 0xbfb8aa3b, v159
	v_fma_f32 v156, v127, v164, v142
	v_fma_f32 v157, v123, v164, v141
	v_fma_f32 v158, v119, v164, v140
	v_fma_f32 v159, v115, v164, v139
	v_exp_f32_e32 v152, v152
	v_exp_f32_e32 v153, v153
	v_exp_f32_e32 v154, v154
	v_exp_f32_e32 v155, v155
	v_mul_f32_e32 v150, 0xbfb8aa3b, v147
	v_mul_f32_e32 v147, 0xbfb8aa3b, v163
	v_fma_f32 v160, v128, v164, v146
	v_fma_f32 v161, v124, v164, v145
	v_fma_f32 v162, v120, v164, v144
	v_fma_f32 v163, v116, v164, v143
	v_exp_f32_e32 v156, v156
	v_exp_f32_e32 v157, v157
	v_exp_f32_e32 v158, v158
	v_exp_f32_e32 v159, v159
	v_fma_f32 v166, v129, v164, v150
	v_fma_f32 v167, v125, v164, v149
	v_fma_f32 v168, v121, v164, v148
	v_fma_f32 v164, v117, v164, v147
	v_exp_f32_e32 v160, v160
	v_exp_f32_e32 v161, v161
	v_exp_f32_e32 v162, v162
	v_exp_f32_e32 v163, v163
	v_exp_f32_e32 v166, v166
	v_exp_f32_e32 v167, v167
	v_exp_f32_e32 v168, v168
	v_exp_f32_e32 v164, v164
	v_fma_f32 v152, v152, v229, v229 clamp
	v_fma_f32 v153, v153, v229, v229 clamp
	v_fma_f32 v154, v154, v229, v229 clamp
	v_fma_f32 v155, v155, v229, v229 clamp
	v_fma_f32 v156, v156, v229, v229 clamp
	v_fma_f32 v157, v157, v229, v229 clamp
	v_fma_f32 v158, v158, v229, v229 clamp
	v_fma_f32 v159, v159, v229, v229 clamp
	v_rcp_f32_e32 v152, v152
	v_rcp_f32_e32 v153, v153
	v_rcp_f32_e32 v154, v154
	v_rcp_f32_e32 v155, v155
	v_fma_f32 v160, v160, v229, v229 clamp
	v_fma_f32 v161, v161, v229, v229 clamp
	v_fma_f32 v162, v162, v229, v229 clamp
	v_fma_f32 v163, v163, v229, v229 clamp
	v_rcp_f32_e32 v156, v156
	v_rcp_f32_e32 v157, v157
	v_rcp_f32_e32 v158, v158
	v_rcp_f32_e32 v159, v159
	v_fma_f32 v166, v166, v229, v229 clamp
	v_fma_f32 v167, v167, v229, v229 clamp
	v_fma_f32 v168, v168, v229, v229 clamp
	v_fma_f32 v164, v164, v229, v229 clamp
	v_rcp_f32_e32 v160, v160
	v_rcp_f32_e32 v161, v161
	v_rcp_f32_e32 v162, v162
	v_rcp_f32_e32 v163, v163
	v_rcp_f32_e32 v166, v166
	v_rcp_f32_e32 v167, v167
	v_rcp_f32_e32 v168, v168
	v_rcp_f32_e32 v164, v164
	v_rndne_f32_e32 v152, v152
	v_rndne_f32_e32 v153, v153
	v_rndne_f32_e32 v154, v154
	v_rndne_f32_e32 v155, v155
	v_rndne_f32_e32 v156, v156
	v_rndne_f32_e32 v157, v157
	v_rndne_f32_e32 v158, v158
	v_rndne_f32_e32 v159, v159
	v_rndne_f32_e32 v160, v160
	v_rndne_f32_e32 v161, v161
	v_rndne_f32_e32 v162, v162
	v_rndne_f32_e32 v163, v163
	v_cvt_pk_u8_f32 v152, v152, 0, 0
	v_cvt_pk_u8_f32 v153, v153, 0, 0
	v_cvt_pk_u8_f32 v154, v154, 0, 0
	v_cvt_pk_u8_f32 v155, v155, 0, 0
	v_rndne_f32_e32 v166, v166
	v_rndne_f32_e32 v167, v167
	v_rndne_f32_e32 v168, v168
	v_rndne_f32_e32 v164, v164
	v_cvt_pk_u8_f32 v152, v156, 1, v152
	v_cvt_pk_u8_f32 v153, v157, 1, v153
	v_cvt_pk_u8_f32 v154, v158, 1, v154
	v_cvt_pk_u8_f32 v155, v159, 1, v155
	v_cvt_pk_u8_f32 v152, v160, 2, v152
	v_cvt_pk_u8_f32 v153, v161, 2, v153
	v_cvt_pk_u8_f32 v154, v162, 2, v154
	v_cvt_pk_u8_f32 v155, v163, 2, v155
	v_cvt_pk_u8_f32 v152, v166, 3, v152
	v_cvt_pk_u8_f32 v153, v167, 3, v153
	v_cvt_pk_u8_f32 v154, v168, 3, v154
	v_cvt_pk_u8_f32 v155, v164, 3, v155
	global_store_dwordx4 v202, v[152:155], s[2:3]
	s_nop 1
	v_mul_f32_e32 v152, 0xbfb8aa3b, v165
	v_fma_f32 v153, v110, v152, v138
	v_fma_f32 v154, v106, v152, v137
	v_fma_f32 v155, v102, v152, v136
	v_fma_f32 v156, v98, v152, v131
	v_fma_f32 v157, v111, v152, v142
	v_fma_f32 v158, v107, v152, v141
	v_fma_f32 v159, v103, v152, v140
	v_fma_f32 v160, v99, v152, v139
	v_fma_f32 v161, v112, v152, v146
	v_fma_f32 v162, v108, v152, v145
	v_fma_f32 v163, v104, v152, v144
	v_fma_f32 v164, v100, v152, v143
	v_fma_f32 v165, v113, v152, v150
	v_fma_f32 v166, v109, v152, v149
	v_fma_f32 v167, v105, v152, v148
	v_fma_f32 v152, v101, v152, v147
	v_exp_f32_e32 v153, v153
	v_exp_f32_e32 v157, v157
	v_exp_f32_e32 v154, v154
	v_exp_f32_e32 v155, v155
	v_exp_f32_e32 v156, v156
	v_exp_f32_e32 v152, v152
	v_exp_f32_e32 v158, v158
	v_exp_f32_e32 v159, v159
	v_exp_f32_e32 v160, v160
	v_exp_f32_e32 v161, v161
	v_exp_f32_e32 v162, v162
	v_exp_f32_e32 v163, v163
	v_exp_f32_e32 v164, v164
	v_fma_f32 v153, v153, v229, v229 clamp
	v_exp_f32_e32 v165, v165
	v_exp_f32_e32 v166, v166
	v_exp_f32_e32 v167, v167
	v_fma_f32 v157, v157, v229, v229 clamp
	v_fma_f32 v154, v154, v229, v229 clamp
	v_fma_f32 v155, v155, v229, v229 clamp
	v_fma_f32 v156, v156, v229, v229 clamp
	v_fma_f32 v152, v152, v229, v229 clamp
	v_rcp_f32_e32 v153, v153
	v_rcp_f32_e32 v157, v157
	v_rcp_f32_e32 v154, v154
	v_rcp_f32_e32 v155, v155
	v_rcp_f32_e32 v156, v156
	v_rcp_f32_e32 v152, v152
	v_fma_f32 v158, v158, v229, v229 clamp
	v_fma_f32 v159, v159, v229, v229 clamp
	v_fma_f32 v160, v160, v229, v229 clamp
	v_fma_f32 v161, v161, v229, v229 clamp
	v_fma_f32 v162, v162, v229, v229 clamp
	v_fma_f32 v163, v163, v229, v229 clamp
	v_fma_f32 v164, v164, v229, v229 clamp
	v_rcp_f32_e32 v158, v158
	v_rcp_f32_e32 v159, v159
	v_rcp_f32_e32 v160, v160
	v_fma_f32 v165, v165, v229, v229 clamp
	v_fma_f32 v166, v166, v229, v229 clamp
	v_fma_f32 v167, v167, v229, v229 clamp
	v_rcp_f32_e32 v161, v161
	v_rcp_f32_e32 v162, v162
	v_rcp_f32_e32 v163, v163
	v_rcp_f32_e32 v164, v164
	v_rndne_f32_e32 v153, v153
	v_rcp_f32_e32 v165, v165
	v_rcp_f32_e32 v166, v166
	v_rcp_f32_e32 v167, v167
	v_rndne_f32_e32 v157, v157
	v_rndne_f32_e32 v154, v154
	v_rndne_f32_e32 v155, v155
	v_rndne_f32_e32 v156, v156
	v_rndne_f32_e32 v152, v152
	v_max_f32_e32 v168, 1.0, v152
	v_cvt_pk_u8_f32 v152, v153, 0, 0
	v_rndne_f32_e32 v158, v158
	v_rndne_f32_e32 v159, v159
	v_rndne_f32_e32 v160, v160
	v_cvt_pk_u8_f32 v152, v157, 1, v152
	v_cvt_pk_u8_f32 v153, v154, 0, 0
	v_cvt_pk_u8_f32 v154, v155, 0, 0
	v_cvt_pk_u8_f32 v155, v156, 0, 0
	ds_read2_b32 v[156:157], v151 offset0:32 offset1:48
	v_rndne_f32_e32 v161, v161
	v_rndne_f32_e32 v162, v162
	v_rndne_f32_e32 v163, v163
	v_rndne_f32_e32 v164, v164
	v_rndne_f32_e32 v165, v165
	v_rndne_f32_e32 v166, v166
	v_rndne_f32_e32 v167, v167
	v_cvt_pk_u8_f32 v153, v158, 1, v153
	v_cvt_pk_u8_f32 v154, v159, 1, v154
	v_cvt_pk_u8_f32 v155, v160, 1, v155
	v_cvt_pk_u8_f32 v152, v161, 2, v152
	v_cvt_pk_u8_f32 v153, v162, 2, v153
	v_cvt_pk_u8_f32 v154, v163, 2, v154
	v_cvt_pk_u8_f32 v155, v164, 2, v155
	v_cvt_pk_u8_f32 v152, v165, 3, v152
	v_cvt_pk_u8_f32 v153, v166, 3, v153
	v_cvt_pk_u8_f32 v154, v167, 3, v154
	v_cvt_pk_u8_f32 v155, v168, 3, v155
	global_store_dwordx4 v202, v[152:155], s[2:3] offset:1024
	s_waitcnt lgkmcnt(0)
	s_nop 0
	v_mul_f32_e32 v152, 0xbfb8aa3b, v156
	v_fma_f32 v153, v94, v152, v138
	v_fma_f32 v154, v90, v152, v137
	v_fma_f32 v155, v86, v152, v136
	v_fma_f32 v156, v82, v152, v131
	v_fma_f32 v158, v95, v152, v142
	v_fma_f32 v159, v91, v152, v141
	v_fma_f32 v160, v87, v152, v140
	v_fma_f32 v161, v83, v152, v139
	v_fma_f32 v162, v96, v152, v146
	v_fma_f32 v163, v92, v152, v145
	v_fma_f32 v164, v88, v152, v144
	v_fma_f32 v165, v84, v152, v143
	v_fma_f32 v166, v97, v152, v150
	v_fma_f32 v167, v93, v152, v149
	v_fma_f32 v168, v89, v152, v148
	v_fma_f32 v152, v85, v152, v147
	v_exp_f32_e32 v153, v153
	v_exp_f32_e32 v154, v154
	v_exp_f32_e32 v155, v155
	v_exp_f32_e32 v156, v156
	v_exp_f32_e32 v158, v158
	v_exp_f32_e32 v159, v159
	v_exp_f32_e32 v160, v160
	v_exp_f32_e32 v161, v161
	v_exp_f32_e32 v152, v152
	v_exp_f32_e32 v162, v162
	v_exp_f32_e32 v163, v163
	v_exp_f32_e32 v164, v164
	v_exp_f32_e32 v165, v165
	v_exp_f32_e32 v166, v166
	v_exp_f32_e32 v167, v167
	v_exp_f32_e32 v168, v168
	v_fma_f32 v153, v153, v229, v229 clamp
	v_fma_f32 v154, v154, v229, v229 clamp
	v_fma_f32 v155, v155, v229, v229 clamp
	v_fma_f32 v156, v156, v229, v229 clamp
	v_fma_f32 v158, v158, v229, v229 clamp
	v_fma_f32 v159, v159, v229, v229 clamp
	v_fma_f32 v160, v160, v229, v229 clamp
	v_fma_f32 v161, v161, v229, v229 clamp
	v_fma_f32 v152, v152, v229, v229 clamp
	v_rcp_f32_e32 v153, v153
	v_rcp_f32_e32 v154, v154
	v_rcp_f32_e32 v155, v155
	v_rcp_f32_e32 v156, v156
	v_fma_f32 v162, v162, v229, v229 clamp
	v_fma_f32 v163, v163, v229, v229 clamp
	v_fma_f32 v164, v164, v229, v229 clamp
	v_fma_f32 v165, v165, v229, v229 clamp
	v_rcp_f32_e32 v158, v158
	v_rcp_f32_e32 v159, v159
	v_rcp_f32_e32 v160, v160
	v_rcp_f32_e32 v161, v161
	v_rcp_f32_e32 v152, v152
	v_fma_f32 v166, v166, v229, v229 clamp
	v_fma_f32 v167, v167, v229, v229 clamp
	v_fma_f32 v168, v168, v229, v229 clamp
	v_rcp_f32_e32 v162, v162
	v_rcp_f32_e32 v163, v163
	v_rcp_f32_e32 v164, v164
	v_rcp_f32_e32 v165, v165
	v_rcp_f32_e32 v166, v166
	v_rcp_f32_e32 v167, v167
	v_rcp_f32_e32 v168, v168
	v_rndne_f32_e32 v153, v153
	v_rndne_f32_e32 v154, v154
	v_rndne_f32_e32 v155, v155
	v_rndne_f32_e32 v156, v156
	v_rndne_f32_e32 v158, v158
	v_rndne_f32_e32 v159, v159
	v_rndne_f32_e32 v160, v160
	v_rndne_f32_e32 v161, v161
	v_rndne_f32_e32 v152, v152
	v_rndne_f32_e32 v162, v162
	v_rndne_f32_e32 v163, v163
	v_rndne_f32_e32 v164, v164
	v_rndne_f32_e32 v165, v165
	v_max_f32_e32 v169, 1.0, v152
	v_cvt_pk_u8_f32 v152, v153, 0, 0
	v_cvt_pk_u8_f32 v153, v154, 0, 0
	v_cvt_pk_u8_f32 v154, v155, 0, 0
	v_cvt_pk_u8_f32 v155, v156, 0, 0
	v_rndne_f32_e32 v166, v166
	v_rndne_f32_e32 v167, v167
	v_rndne_f32_e32 v168, v168
	v_cvt_pk_u8_f32 v152, v158, 1, v152
	v_cvt_pk_u8_f32 v153, v159, 1, v153
	v_cvt_pk_u8_f32 v154, v160, 1, v154
	v_cvt_pk_u8_f32 v155, v161, 1, v155
	v_cvt_pk_u8_f32 v152, v162, 2, v152
	v_cvt_pk_u8_f32 v153, v163, 2, v153
	v_cvt_pk_u8_f32 v154, v164, 2, v154
	v_cvt_pk_u8_f32 v155, v165, 2, v155
	v_cvt_pk_u8_f32 v152, v166, 3, v152
	v_cvt_pk_u8_f32 v153, v167, 3, v153
	v_cvt_pk_u8_f32 v154, v168, 3, v154
	v_cvt_pk_u8_f32 v155, v169, 3, v155
	global_store_dwordx4 v202, v[152:155], s[2:3] offset:2048
	s_nop 1
	v_mul_f32_e32 v152, 0xbfb8aa3b, v157
	v_fma_f32 v153, v78, v152, v138
	v_fma_f32 v154, v74, v152, v137
	v_fma_f32 v155, v70, v152, v136
	v_fma_f32 v156, v66, v152, v131
	v_fma_f32 v157, v79, v152, v142
	v_fma_f32 v158, v75, v152, v141
	v_fma_f32 v159, v71, v152, v140
	v_fma_f32 v160, v67, v152, v139
	v_fma_f32 v161, v80, v152, v146
	v_fma_f32 v162, v76, v152, v145
	v_fma_f32 v163, v72, v152, v144
	v_fma_f32 v164, v68, v152, v143
	v_fma_f32 v165, v81, v152, v150
	v_fma_f32 v166, v77, v152, v149
	v_fma_f32 v167, v73, v152, v148
	v_fma_f32 v152, v69, v152, v147
	v_exp_f32_e32 v153, v153
	v_exp_f32_e32 v157, v157
	v_exp_f32_e32 v154, v154
	v_exp_f32_e32 v155, v155
	v_exp_f32_e32 v156, v156
	v_exp_f32_e32 v152, v152
	v_exp_f32_e32 v158, v158
	v_exp_f32_e32 v159, v159
	v_exp_f32_e32 v160, v160
	v_exp_f32_e32 v161, v161
	v_exp_f32_e32 v162, v162
	v_exp_f32_e32 v163, v163
	v_exp_f32_e32 v164, v164
	v_fma_f32 v153, v153, v229, v229 clamp
	v_exp_f32_e32 v165, v165
	v_exp_f32_e32 v166, v166
	v_exp_f32_e32 v167, v167
	v_fma_f32 v157, v157, v229, v229 clamp
	v_fma_f32 v154, v154, v229, v229 clamp
	v_fma_f32 v155, v155, v229, v229 clamp
	v_fma_f32 v156, v156, v229, v229 clamp
	v_fma_f32 v152, v152, v229, v229 clamp
	v_rcp_f32_e32 v153, v153
	v_rcp_f32_e32 v157, v157
	v_rcp_f32_e32 v154, v154
	v_rcp_f32_e32 v155, v155
	v_rcp_f32_e32 v156, v156
	v_rcp_f32_e32 v152, v152
	v_fma_f32 v158, v158, v229, v229 clamp
	v_fma_f32 v159, v159, v229, v229 clamp
	v_fma_f32 v160, v160, v229, v229 clamp
	v_fma_f32 v161, v161, v229, v229 clamp
	v_fma_f32 v162, v162, v229, v229 clamp
	v_fma_f32 v163, v163, v229, v229 clamp
	v_fma_f32 v164, v164, v229, v229 clamp
	v_rcp_f32_e32 v158, v158
	v_rcp_f32_e32 v159, v159
	v_rcp_f32_e32 v160, v160
	v_fma_f32 v165, v165, v229, v229 clamp
	v_fma_f32 v166, v166, v229, v229 clamp
	v_fma_f32 v167, v167, v229, v229 clamp
	v_rcp_f32_e32 v161, v161
	v_rcp_f32_e32 v162, v162
	v_rcp_f32_e32 v163, v163
	v_rcp_f32_e32 v164, v164
	v_rndne_f32_e32 v153, v153
	v_rcp_f32_e32 v165, v165
	v_rcp_f32_e32 v166, v166
	v_rcp_f32_e32 v167, v167
	v_rndne_f32_e32 v157, v157
	v_rndne_f32_e32 v154, v154
	v_rndne_f32_e32 v155, v155
	v_rndne_f32_e32 v156, v156
	v_rndne_f32_e32 v152, v152
	v_max_f32_e32 v168, 1.0, v152
	v_cvt_pk_u8_f32 v152, v153, 0, 0
	v_rndne_f32_e32 v158, v158
	v_rndne_f32_e32 v159, v159
	v_rndne_f32_e32 v160, v160
	v_cvt_pk_u8_f32 v152, v157, 1, v152
	v_cvt_pk_u8_f32 v153, v154, 0, 0
	v_cvt_pk_u8_f32 v154, v155, 0, 0
	v_cvt_pk_u8_f32 v155, v156, 0, 0
	ds_read2_b32 v[156:157], v151 offset0:128 offset1:144
	v_rndne_f32_e32 v161, v161
	v_rndne_f32_e32 v162, v162
	v_rndne_f32_e32 v163, v163
	v_rndne_f32_e32 v164, v164
	v_rndne_f32_e32 v165, v165
	v_rndne_f32_e32 v166, v166
	v_rndne_f32_e32 v167, v167
	v_cvt_pk_u8_f32 v153, v158, 1, v153
	v_cvt_pk_u8_f32 v154, v159, 1, v154
	v_cvt_pk_u8_f32 v155, v160, 1, v155
	v_cvt_pk_u8_f32 v152, v161, 2, v152
	v_cvt_pk_u8_f32 v153, v162, 2, v153
	v_cvt_pk_u8_f32 v154, v163, 2, v154
	v_cvt_pk_u8_f32 v155, v164, 2, v155
	v_cvt_pk_u8_f32 v152, v165, 3, v152
	v_cvt_pk_u8_f32 v153, v166, 3, v153
	v_cvt_pk_u8_f32 v154, v167, 3, v154
	v_cvt_pk_u8_f32 v155, v168, 3, v155
	global_store_dwordx4 v202, v[152:155], s[2:3] offset:3072
	s_movk_i32 s2, 0x1000
	v_add_co_u32_e32 v132, vcc, s2, v132
	s_waitcnt lgkmcnt(0)
	v_mul_f32_e32 v152, 0xbfb8aa3b, v156
	v_fma_f32 v153, v62, v152, v138
	v_fma_f32 v154, v58, v152, v137
	v_fma_f32 v155, v54, v152, v136
	v_fma_f32 v156, v50, v152, v131
	v_fma_f32 v158, v63, v152, v142
	v_fma_f32 v159, v59, v152, v141
	v_fma_f32 v160, v55, v152, v140
	v_fma_f32 v161, v51, v152, v139
	v_fma_f32 v162, v64, v152, v146
	v_fma_f32 v163, v60, v152, v145
	v_fma_f32 v164, v56, v152, v144
	v_fma_f32 v165, v52, v152, v143
	v_fma_f32 v166, v65, v152, v150
	v_fma_f32 v167, v61, v152, v149
	v_fma_f32 v168, v57, v152, v148
	v_fma_f32 v152, v53, v152, v147
	v_exp_f32_e32 v153, v153
	v_exp_f32_e32 v154, v154
	v_exp_f32_e32 v155, v155
	v_exp_f32_e32 v156, v156
	v_exp_f32_e32 v158, v158
	v_exp_f32_e32 v159, v159
	v_exp_f32_e32 v160, v160
	v_exp_f32_e32 v161, v161
	v_exp_f32_e32 v152, v152
	v_exp_f32_e32 v162, v162
	v_exp_f32_e32 v163, v163
	v_exp_f32_e32 v164, v164
	v_exp_f32_e32 v165, v165
	v_exp_f32_e32 v166, v166
	v_exp_f32_e32 v167, v167
	v_exp_f32_e32 v168, v168
	v_fma_f32 v153, v153, v229, v229 clamp
	v_fma_f32 v154, v154, v229, v229 clamp
	v_fma_f32 v155, v155, v229, v229 clamp
	v_fma_f32 v156, v156, v229, v229 clamp
	v_fma_f32 v158, v158, v229, v229 clamp
	v_fma_f32 v159, v159, v229, v229 clamp
	v_fma_f32 v160, v160, v229, v229 clamp
	v_fma_f32 v161, v161, v229, v229 clamp
	v_fma_f32 v152, v152, v229, v229 clamp
	v_rcp_f32_e32 v153, v153
	v_rcp_f32_e32 v154, v154
	v_rcp_f32_e32 v155, v155
	v_rcp_f32_e32 v156, v156
	v_fma_f32 v162, v162, v229, v229 clamp
	v_fma_f32 v163, v163, v229, v229 clamp
	v_fma_f32 v164, v164, v229, v229 clamp
	v_fma_f32 v165, v165, v229, v229 clamp
	v_rcp_f32_e32 v158, v158
	v_rcp_f32_e32 v159, v159
	v_rcp_f32_e32 v160, v160
	v_rcp_f32_e32 v161, v161
	v_rcp_f32_e32 v152, v152
	v_fma_f32 v166, v166, v229, v229 clamp
	v_fma_f32 v167, v167, v229, v229 clamp
	v_fma_f32 v168, v168, v229, v229 clamp
	v_rcp_f32_e32 v162, v162
	v_rcp_f32_e32 v163, v163
	v_rcp_f32_e32 v164, v164
	v_rcp_f32_e32 v165, v165
	v_rcp_f32_e32 v166, v166
	v_rcp_f32_e32 v167, v167
	v_rcp_f32_e32 v168, v168
	v_rndne_f32_e32 v153, v153
	v_rndne_f32_e32 v154, v154
	v_rndne_f32_e32 v155, v155
	v_rndne_f32_e32 v156, v156
	v_rndne_f32_e32 v158, v158
	v_rndne_f32_e32 v159, v159
	v_rndne_f32_e32 v160, v160
	v_rndne_f32_e32 v161, v161
	v_rndne_f32_e32 v152, v152
	v_rndne_f32_e32 v162, v162
	v_rndne_f32_e32 v163, v163
	v_rndne_f32_e32 v164, v164
	v_rndne_f32_e32 v165, v165
	v_max_f32_e32 v169, 1.0, v152
	v_cvt_pk_u8_f32 v152, v153, 0, 0
	v_cvt_pk_u8_f32 v153, v154, 0, 0
	v_cvt_pk_u8_f32 v154, v155, 0, 0
	v_cvt_pk_u8_f32 v155, v156, 0, 0
	v_rndne_f32_e32 v166, v166
	v_rndne_f32_e32 v167, v167
	v_rndne_f32_e32 v168, v168
	v_cvt_pk_u8_f32 v152, v158, 1, v152
	v_cvt_pk_u8_f32 v153, v159, 1, v153
	v_cvt_pk_u8_f32 v154, v160, 1, v154
	v_cvt_pk_u8_f32 v155, v161, 1, v155
	v_cvt_pk_u8_f32 v152, v162, 2, v152
	v_cvt_pk_u8_f32 v153, v163, 2, v153
	v_cvt_pk_u8_f32 v154, v164, 2, v154
	v_cvt_pk_u8_f32 v155, v165, 2, v155
	v_cvt_pk_u8_f32 v152, v166, 3, v152
	v_cvt_pk_u8_f32 v153, v167, 3, v153
	v_cvt_pk_u8_f32 v154, v168, 3, v154
	v_cvt_pk_u8_f32 v155, v169, 3, v155
	v_addc_co_u32_e32 v133, vcc, 0, v133, vcc
	global_store_dwordx4 v[132:133], v[152:155], off
	s_nop 1
	v_mul_f32_e32 v152, 0xbfb8aa3b, v157
	v_fma_f32 v153, v46, v152, v138
	v_fma_f32 v154, v42, v152, v137
	v_fma_f32 v155, v38, v152, v136
	v_fma_f32 v156, v34, v152, v131
	v_fma_f32 v157, v47, v152, v142
	v_fma_f32 v158, v43, v152, v141
	v_fma_f32 v159, v39, v152, v140
	v_fma_f32 v160, v35, v152, v139
	v_fma_f32 v161, v48, v152, v146
	v_fma_f32 v162, v44, v152, v145
	v_fma_f32 v163, v40, v152, v144
	v_fma_f32 v164, v36, v152, v143
	v_fma_f32 v165, v49, v152, v150
	v_fma_f32 v166, v45, v152, v149
	v_fma_f32 v167, v41, v152, v148
	v_fma_f32 v152, v37, v152, v147
	v_exp_f32_e32 v153, v153
	v_exp_f32_e32 v157, v157
	v_exp_f32_e32 v154, v154
	v_exp_f32_e32 v155, v155
	v_exp_f32_e32 v156, v156
	v_exp_f32_e32 v152, v152
	v_exp_f32_e32 v158, v158
	v_exp_f32_e32 v159, v159
	v_exp_f32_e32 v160, v160
	v_fma_f32 v153, v153, v229, v229 clamp
	v_exp_f32_e32 v161, v161
	v_exp_f32_e32 v162, v162
	v_exp_f32_e32 v163, v163
	v_exp_f32_e32 v164, v164
	v_fma_f32 v157, v157, v229, v229 clamp
	v_fma_f32 v154, v154, v229, v229 clamp
	v_fma_f32 v155, v155, v229, v229 clamp
	v_fma_f32 v156, v156, v229, v229 clamp
	v_fma_f32 v152, v152, v229, v229 clamp
	v_rcp_f32_e32 v153, v153
	v_exp_f32_e32 v165, v165
	v_exp_f32_e32 v166, v166
	v_exp_f32_e32 v167, v167
	v_rcp_f32_e32 v157, v157
	v_rcp_f32_e32 v154, v154
	v_rcp_f32_e32 v155, v155
	v_rcp_f32_e32 v156, v156
	v_rcp_f32_e32 v152, v152
	v_fma_f32 v158, v158, v229, v229 clamp
	v_fma_f32 v159, v159, v229, v229 clamp
	v_fma_f32 v160, v160, v229, v229 clamp
	v_fma_f32 v161, v161, v229, v229 clamp
	v_fma_f32 v162, v162, v229, v229 clamp
	v_fma_f32 v163, v163, v229, v229 clamp
	v_fma_f32 v164, v164, v229, v229 clamp
	v_rcp_f32_e32 v158, v158
	v_rcp_f32_e32 v159, v159
	v_rcp_f32_e32 v160, v160
	v_rndne_f32_e32 v153, v153
	v_fma_f32 v165, v165, v229, v229 clamp
	v_fma_f32 v166, v166, v229, v229 clamp
	v_fma_f32 v167, v167, v229, v229 clamp
	v_rcp_f32_e32 v161, v161
	v_rcp_f32_e32 v162, v162
	v_rcp_f32_e32 v163, v163
	v_rcp_f32_e32 v164, v164
	v_rndne_f32_e32 v157, v157
	v_rndne_f32_e32 v154, v154
	v_rndne_f32_e32 v155, v155
	v_rndne_f32_e32 v156, v156
	v_rndne_f32_e32 v152, v152
	v_rcp_f32_e32 v165, v165
	v_rcp_f32_e32 v166, v166
	v_rcp_f32_e32 v167, v167
	v_max_f32_e32 v168, 1.0, v152
	v_cvt_pk_u8_f32 v152, v153, 0, 0
	v_cvt_pk_u8_f32 v152, v157, 1, v152
	v_cvt_pk_u8_f32 v153, v154, 0, 0
	v_cvt_pk_u8_f32 v154, v155, 0, 0
	v_cvt_pk_u8_f32 v155, v156, 0, 0
	ds_read2_b32 v[156:157], v151 offset0:160 offset1:176
	v_rndne_f32_e32 v158, v158
	v_rndne_f32_e32 v159, v159
	v_rndne_f32_e32 v160, v160
	v_rndne_f32_e32 v161, v161
	v_rndne_f32_e32 v162, v162
	v_rndne_f32_e32 v163, v163
	v_rndne_f32_e32 v164, v164
	v_rndne_f32_e32 v165, v165
	v_rndne_f32_e32 v166, v166
	v_rndne_f32_e32 v167, v167
	v_cvt_pk_u8_f32 v153, v158, 1, v153
	v_cvt_pk_u8_f32 v154, v159, 1, v154
	v_cvt_pk_u8_f32 v151, v160, 1, v155
	v_cvt_pk_u8_f32 v152, v161, 2, v152
	v_cvt_pk_u8_f32 v153, v162, 2, v153
	v_cvt_pk_u8_f32 v154, v163, 2, v154
	v_cvt_pk_u8_f32 v151, v164, 2, v151
	v_cvt_pk_u8_f32 v152, v165, 3, v152
	v_cvt_pk_u8_f32 v153, v166, 3, v153
	v_cvt_pk_u8_f32 v154, v167, 3, v154
	v_cvt_pk_u8_f32 v155, v168, 3, v151
	s_waitcnt lgkmcnt(0)
	v_mul_f32_e32 v151, 0xbfb8aa3b, v156
	global_store_dwordx4 v[132:133], v[152:155], off offset:1024
	v_fma_f32 v160, v19, v151, v139
	v_fma_f32 v164, v20, v151, v143
	v_fma_f32 v155, v18, v151, v131
	v_exp_f32_e32 v155, v155
	v_exp_f32_e32 v160, v160
	v_fma_f32 v152, v30, v151, v138
	v_fma_f32 v153, v26, v151, v137
	v_fma_f32 v154, v22, v151, v136
	v_fma_f32 v156, v31, v151, v142
	v_fma_f32 v158, v27, v151, v141
	v_fma_f32 v159, v23, v151, v140
	v_fma_f32 v161, v32, v151, v146
	v_fma_f32 v162, v28, v151, v145
	v_fma_f32 v163, v24, v151, v144
	v_fma_f32 v165, v33, v151, v150
	v_fma_f32 v166, v29, v151, v149
	v_fma_f32 v167, v25, v151, v148
	v_fma_f32 v151, v21, v151, v147
	v_exp_f32_e32 v164, v164
	v_exp_f32_e32 v151, v151
	v_fma_f32 v155, v155, v229, v229 clamp
	v_fma_f32 v160, v160, v229, v229 clamp
	v_rcp_f32_e32 v155, v155
	v_fma_f32 v164, v164, v229, v229 clamp
	v_rcp_f32_e32 v160, v160
	v_fma_f32 v151, v151, v229, v229 clamp
	v_rcp_f32_e32 v164, v164
	v_rcp_f32_e32 v151, v151
	v_rndne_f32_e32 v155, v155
	v_rndne_f32_e32 v160, v160
	v_rndne_f32_e32 v164, v164
	v_cvt_pk_u8_f32 v155, v155, 0, 0
	v_rndne_f32_e32 v151, v151
	v_cvt_pk_u8_f32 v155, v160, 1, v155
	v_cvt_pk_u8_f32 v155, v164, 2, v155
	v_cvt_pk_u8_f32 v155, v151, 3, v155
	v_mul_f32_e32 v151, 0xbfb8aa3b, v157
	v_fmac_f32_e32 v136, v6, v151
	v_fmac_f32_e32 v140, v7, v151
	v_exp_f32_e32 v136, v136
	v_fmac_f32_e32 v144, v8, v151
	v_exp_f32_e32 v140, v140
	v_fmac_f32_e32 v148, v9, v151
	v_exp_f32_e32 v144, v144
	v_fmac_f32_e32 v139, v3, v151
	v_exp_f32_e32 v148, v148
	v_fmac_f32_e32 v138, v14, v151
	v_fmac_f32_e32 v137, v10, v151
	v_fmac_f32_e32 v131, v2, v151
	v_fmac_f32_e32 v143, v4, v151
	v_exp_f32_e32 v139, v139
	v_fma_f32 v136, v136, v229, v229 clamp
	v_exp_f32_e32 v152, v152
	v_exp_f32_e32 v153, v153
	v_exp_f32_e32 v154, v154
	v_fmac_f32_e32 v142, v15, v151
	v_fmac_f32_e32 v141, v11, v151
	v_fmac_f32_e32 v147, v5, v151
	v_exp_f32_e32 v138, v138
	v_exp_f32_e32 v137, v137
	v_exp_f32_e32 v131, v131
	v_exp_f32_e32 v143, v143
	v_fma_f32 v140, v140, v229, v229 clamp
	v_rcp_f32_e32 v136, v136
	v_exp_f32_e32 v156, v156
	v_exp_f32_e32 v158, v158
	v_exp_f32_e32 v159, v159
	v_fmac_f32_e32 v146, v16, v151
	v_fmac_f32_e32 v145, v12, v151
	v_exp_f32_e32 v142, v142
	v_exp_f32_e32 v141, v141
	v_exp_f32_e32 v147, v147
	v_fma_f32 v144, v144, v229, v229 clamp
	v_rcp_f32_e32 v140, v140
	v_exp_f32_e32 v161, v161
	v_exp_f32_e32 v162, v162
	v_exp_f32_e32 v163, v163
	v_fmac_f32_e32 v150, v17, v151
	v_fmac_f32_e32 v149, v13, v151
	v_exp_f32_e32 v146, v146
	v_exp_f32_e32 v145, v145
	v_fma_f32 v148, v148, v229, v229 clamp
	v_rcp_f32_e32 v144, v144
	v_exp_f32_e32 v165, v165
	v_exp_f32_e32 v166, v166
	v_exp_f32_e32 v167, v167
	v_exp_f32_e32 v150, v150
	v_exp_f32_e32 v149, v149
	v_fma_f32 v139, v139, v229, v229 clamp
	v_rcp_f32_e32 v148, v148
	v_fma_f32 v152, v152, v229, v229 clamp
	v_fma_f32 v153, v153, v229, v229 clamp
	v_fma_f32 v154, v154, v229, v229 clamp
	v_fma_f32 v138, v138, v229, v229 clamp
	v_fma_f32 v137, v137, v229, v229 clamp
	v_fma_f32 v131, v131, v229, v229 clamp
	v_fma_f32 v143, v143, v229, v229 clamp
	v_rcp_f32_e32 v139, v139
	v_rndne_f32_e32 v136, v136
	v_fma_f32 v156, v156, v229, v229 clamp
	v_fma_f32 v158, v158, v229, v229 clamp
	v_fma_f32 v159, v159, v229, v229 clamp
	v_rcp_f32_e32 v152, v152
	v_rcp_f32_e32 v153, v153
	v_rcp_f32_e32 v154, v154
	v_fma_f32 v142, v142, v229, v229 clamp
	v_fma_f32 v141, v141, v229, v229 clamp
	v_fma_f32 v147, v147, v229, v229 clamp
	v_rcp_f32_e32 v138, v138
	v_rcp_f32_e32 v137, v137
	v_rcp_f32_e32 v131, v131
	v_rcp_f32_e32 v143, v143
	v_max_f32_e32 v151, 1.0, v136
	v_rndne_f32_e32 v136, v140
	v_fma_f32 v161, v161, v229, v229 clamp
	v_fma_f32 v162, v162, v229, v229 clamp
	v_fma_f32 v163, v163, v229, v229 clamp
	v_rcp_f32_e32 v156, v156
	v_rcp_f32_e32 v158, v158
	v_rcp_f32_e32 v159, v159
	v_fma_f32 v146, v146, v229, v229 clamp
	v_fma_f32 v145, v145, v229, v229 clamp
	v_rcp_f32_e32 v142, v142
	v_rcp_f32_e32 v141, v141
	v_rcp_f32_e32 v147, v147
	v_max_f32_e32 v140, 1.0, v136
	v_rndne_f32_e32 v136, v144
	v_fma_f32 v165, v165, v229, v229 clamp
	v_fma_f32 v166, v166, v229, v229 clamp
	v_fma_f32 v167, v167, v229, v229 clamp
	v_rcp_f32_e32 v161, v161
	v_rcp_f32_e32 v162, v162
	v_rcp_f32_e32 v163, v163
	v_fma_f32 v150, v150, v229, v229 clamp
	v_fma_f32 v149, v149, v229, v229 clamp
	v_rcp_f32_e32 v146, v146
	v_rcp_f32_e32 v145, v145
	v_max_f32_e32 v144, 1.0, v136
	v_rndne_f32_e32 v136, v148
	v_rcp_f32_e32 v165, v165
	v_rcp_f32_e32 v166, v166
	v_rcp_f32_e32 v167, v167
	v_rcp_f32_e32 v150, v150
	v_rcp_f32_e32 v149, v149
	v_max_f32_e32 v148, 1.0, v136
	v_rndne_f32_e32 v136, v139
	v_rndne_f32_e32 v152, v152
	v_rndne_f32_e32 v153, v153
	v_rndne_f32_e32 v154, v154
	v_rndne_f32_e32 v138, v138
	v_rndne_f32_e32 v137, v137
	v_rndne_f32_e32 v131, v131
	v_max_f32_e32 v139, 1.0, v136
	v_rndne_f32_e32 v136, v143
	v_rndne_f32_e32 v156, v156
	v_rndne_f32_e32 v158, v158
	v_rndne_f32_e32 v159, v159
	v_rndne_f32_e32 v142, v142
	v_rndne_f32_e32 v141, v141
	v_max_f32_e32 v143, 1.0, v136
	v_rndne_f32_e32 v136, v147
	v_rndne_f32_e32 v161, v161
	v_rndne_f32_e32 v162, v162
	v_rndne_f32_e32 v163, v163
	v_cvt_pk_u8_f32 v152, v152, 0, 0
	v_cvt_pk_u8_f32 v153, v153, 0, 0
	v_cvt_pk_u8_f32 v154, v154, 0, 0
	v_rndne_f32_e32 v146, v146
	v_rndne_f32_e32 v145, v145
	v_max_f32_e32 v147, 1.0, v136
	v_cvt_pk_u8_f32 v136, v138, 0, 0
	v_cvt_pk_u8_f32 v137, v137, 0, 0
	v_cvt_pk_u8_f32 v138, v151, 0, 0
	v_cvt_pk_u8_f32 v131, v131, 0, 0
	v_rndne_f32_e32 v165, v165
	v_rndne_f32_e32 v166, v166
	v_rndne_f32_e32 v167, v167
	v_cvt_pk_u8_f32 v152, v156, 1, v152
	v_cvt_pk_u8_f32 v153, v158, 1, v153
	v_cvt_pk_u8_f32 v154, v159, 1, v154
	v_rndne_f32_e32 v150, v150
	v_rndne_f32_e32 v149, v149
	v_cvt_pk_u8_f32 v136, v142, 1, v136
	v_cvt_pk_u8_f32 v137, v141, 1, v137
	v_cvt_pk_u8_f32 v138, v140, 1, v138
	v_cvt_pk_u8_f32 v131, v139, 1, v131
	v_cvt_pk_u8_f32 v152, v161, 2, v152
	v_cvt_pk_u8_f32 v153, v162, 2, v153
	v_cvt_pk_u8_f32 v154, v163, 2, v154
	v_cvt_pk_u8_f32 v136, v146, 2, v136
	v_cvt_pk_u8_f32 v137, v145, 2, v137
	v_cvt_pk_u8_f32 v138, v144, 2, v138
	v_cvt_pk_u8_f32 v131, v143, 2, v131
	v_cvt_pk_u8_f32 v152, v165, 3, v152
	v_cvt_pk_u8_f32 v153, v166, 3, v153
	v_cvt_pk_u8_f32 v154, v167, 3, v154
	v_cvt_pk_u8_f32 v136, v150, 3, v136
	v_cvt_pk_u8_f32 v137, v149, 3, v137
	v_cvt_pk_u8_f32 v138, v148, 3, v138
	v_cvt_pk_u8_f32 v139, v147, 3, v131
	global_store_dwordx4 v[132:133], v[152:155], off offset:2048
	global_store_dwordx4 v[132:133], v[136:139], off offset:3072
